# attention gain-max scan: 48 dependent loads replaced by 2 parallel per-lane loads + wave max-reduce
# speedup vs baseline: 1.0115x; 1.0046x over previous
.LBB0_160:
	v_and_b32_e32 v1, 63, v167
	v_lshlrev_b32_e32 v1, 2, v1
	global_load_dword v2, v1, s[90:91]
	global_load_dword v3, v1, s[90:91] offset:128
	s_waitcnt vmcnt(0)
	v_max_f32_e64 v2, |v2|, |v3|
	v_xor_b32_e32 v3, 4, v1
	ds_bpermute_b32 v4, v3, v2
	s_waitcnt lgkmcnt(0)
	v_max_f32_e32 v2, v2, v4
	v_xor_b32_e32 v3, 8, v1
	ds_bpermute_b32 v4, v3, v2
	s_waitcnt lgkmcnt(0)
	v_max_f32_e32 v2, v2, v4
	v_xor_b32_e32 v3, 16, v1
	ds_bpermute_b32 v4, v3, v2
	s_waitcnt lgkmcnt(0)
	v_max_f32_e32 v2, v2, v4
	v_xor_b32_e32 v3, 32, v1
	ds_bpermute_b32 v4, v3, v2
	s_waitcnt lgkmcnt(0)
	v_max_f32_e32 v2, v2, v4
	v_xor_b32_e32 v3, 64, v1
	ds_bpermute_b32 v4, v3, v2
	s_waitcnt lgkmcnt(0)
	v_max_f32_e32 v2, v2, v4
	v_xor_b32_e32 v3, 128, v1
	ds_bpermute_b32 v4, v3, v2
	s_waitcnt lgkmcnt(0)
	v_max_f32_e32 v2, v2, v4
	v_max_f32_e32 v0, v2, v2
